# RS4+prio + second-half K fragments prefetched during the first half P.V tail
# speedup vs baseline: 1.0194x; 1.0021x over previous
.Lv2_back_h1:
	v_mul_f32_e32 v189, v221, v206
	v_fma_f32 v190, s100, v189, v255
	v_fma_f32 v148, v148, v189, -v190
	v_fma_f32 v149, v149, v189, -v190
	v_exp_f32_e32 v148, v148
	v_fma_f32 v150, v150, v189, -v190
	v_exp_f32_e32 v149, v149
	v_fma_f32 v151, v151, v189, -v190
	v_exp_f32_e32 v150, v150
	v_fma_f32 v152, v152, v189, -v190
	v_exp_f32_e32 v151, v151
	v_fma_f32 v153, v153, v189, -v190
	v_exp_f32_e32 v152, v152
	v_fma_f32 v154, v154, v189, -v190
	v_exp_f32_e32 v153, v153
	v_fma_f32 v155, v155, v189, -v190
	v_exp_f32_e32 v154, v154
	v_fma_f32 v156, v156, v189, -v190
	v_exp_f32_e32 v155, v155
	v_fma_f32 v157, v157, v189, -v190
	v_exp_f32_e32 v156, v156
	v_fma_f32 v158, v158, v189, -v190
	v_exp_f32_e32 v157, v157
	v_fma_f32 v159, v159, v189, -v190
	v_exp_f32_e32 v158, v158
	v_fma_f32 v160, v160, v189, -v190
	v_exp_f32_e32 v159, v159
	v_fma_f32 v161, v161, v189, -v190
	v_exp_f32_e32 v160, v160
	v_fma_f32 v162, v162, v189, -v190
	v_exp_f32_e32 v161, v161
	v_fma_f32 v163, v163, v189, -v190
	v_exp_f32_e32 v162, v162
	v_exp_f32_e32 v163, v163
	v_add_f32_e32 v188, v148, v149
	v_add_f32_e32 v189, v150, v151
	v_add_f32_e32 v190, v152, v153
	v_add_f32_e32 v191, v154, v155
	v_add_f32_e32 v192, v156, v157
	v_add_f32_e32 v193, v158, v159
	v_add_f32_e32 v194, v160, v161
	v_add_f32_e32 v195, v162, v163
	v_add_f32_e32 v188, v188, v189
	v_add_f32_e32 v190, v190, v191
	v_add_f32_e32 v192, v192, v193
	v_add_f32_e32 v194, v194, v195
	v_add_f32_e32 v188, v188, v190
	v_add_f32_e32 v192, v192, v194
	v_add_f32_e32 v188, v188, v192
	v_add_f32_e32 v224, v224, v188
	v_cvt_pk_bf16_f32 v155, v154, v155
	v_cvt_pk_bf16_f32 v154, v152, v153
	v_cvt_pk_bf16_f32 v152, v148, v149
	v_cvt_pk_bf16_f32 v153, v150, v151
	v_cvt_pk_bf16_f32 v148, v156, v157
	v_cvt_pk_bf16_f32 v149, v158, v159
	v_cvt_pk_bf16_f32 v150, v160, v161
	v_cvt_pk_bf16_f32 v151, v162, v163
	s_barrier
	s_setprio 0
	s_waitcnt lgkmcnt(2)
	v_mfma_f32_32x32x16_bf16 v[4:19], v[152:155], v[184:187], v[4:19]
	ds_read_b64_tr_b16 v[156:157], v3 offset:33792
	ds_read_b64_tr_b16 v[158:159], v3 offset:37888
	s_waitcnt lgkmcnt(2)
	v_mfma_f32_32x32x16_bf16 v[116:131], v[152:155], v[180:183], v[116:131]
	ds_read_b64_tr_b16 v[160:161], v3 offset:34304
	ds_read_b64_tr_b16 v[162:163], v3 offset:38400
	s_add_i32 m0, s80, 0x4000
	s_nop 0
	global_load_lds_dwordx4 v200, s[86:87]
	s_waitcnt lgkmcnt(2)
	v_mfma_f32_32x32x16_bf16 v[100:115], v[152:155], v[156:159], v[100:115]
	ds_read_b64_tr_b16 v[156:157], v3 offset:34816
	ds_read_b64_tr_b16 v[158:159], v3 offset:38912
	s_waitcnt lgkmcnt(2)
	v_mfma_f32_32x32x16_bf16 v[84:99], v[152:155], v[160:163], v[84:99]
	ds_read_b64_tr_b16 v[160:161], v3 offset:35328
	ds_read_b64_tr_b16 v[162:163], v3 offset:39424
	s_add_i32 m0, s81, 0x10000
	s_nop 0
	global_load_lds_dwordx4 v204, s[2:3]
	s_waitcnt lgkmcnt(2)
	v_mfma_f32_32x32x16_bf16 v[68:83], v[152:155], v[156:159], v[68:83]
	ds_read_b64_tr_b16 v[156:157], v3 offset:35840
	ds_read_b64_tr_b16 v[158:159], v3 offset:39936
	s_waitcnt lgkmcnt(2)
	v_mfma_f32_32x32x16_bf16 v[52:67], v[152:155], v[160:163], v[52:67]
	ds_read_b64_tr_b16 v[160:161], v3 offset:36352
	ds_read_b64_tr_b16 v[162:163], v3 offset:40448
	s_add_u32 s2, s2, 0x80
	s_addc_u32 s3, s3, 0
	s_add_i32 m0, s81, 0x10400
	s_nop 0
	global_load_lds_dwordx4 v204, s[2:3]
	s_waitcnt lgkmcnt(2)
	v_mfma_f32_32x32x16_bf16 v[36:51], v[152:155], v[156:159], v[36:51]
	ds_read_b64_tr_b16 v[156:157], v3 offset:40960
	ds_read_b64_tr_b16 v[158:159], v3 offset:45056
	s_waitcnt lgkmcnt(2)
	v_mfma_f32_32x32x16_bf16 v[20:35], v[152:155], v[160:163], v[20:35]
	ds_read_b64_tr_b16 v[152:153], v3 offset:41472
	ds_read_b64_tr_b16 v[154:155], v3 offset:45568
	s_add_u32 s2, s2, 0x80
	s_addc_u32 s3, s3, 0
	s_add_i32 m0, s81, 0x10800
	s_nop 0
	global_load_lds_dwordx4 v204, s[2:3]
	s_waitcnt lgkmcnt(2)
	v_mfma_f32_32x32x16_bf16 v[4:19], v[148:151], v[156:159], v[4:19]
	ds_read_b64_tr_b16 v[156:157], v3 offset:41984
	ds_read_b64_tr_b16 v[158:159], v3 offset:46080
	s_waitcnt lgkmcnt(2)
	v_mfma_f32_32x32x16_bf16 v[116:131], v[148:151], v[152:155], v[116:131]
	ds_read_b64_tr_b16 v[152:153], v3 offset:42496
	ds_read_b64_tr_b16 v[154:155], v3 offset:46592
	s_add_u32 s2, s2, 0x80
	s_addc_u32 s3, s3, 0
	s_add_i32 m0, s81, 0x10c00
	s_nop 0
	global_load_lds_dwordx4 v204, s[2:3]
	s_waitcnt lgkmcnt(2)
	v_mfma_f32_32x32x16_bf16 v[100:115], v[148:151], v[156:159], v[100:115]
	ds_read_b64_tr_b16 v[156:157], v3 offset:43008
	ds_read_b64_tr_b16 v[158:159], v3 offset:47104
	s_waitcnt lgkmcnt(2)
	v_mfma_f32_32x32x16_bf16 v[84:99], v[148:151], v[152:155], v[84:99]
	ds_read_b64_tr_b16 v[152:153], v3 offset:43520
	ds_read_b64_tr_b16 v[154:155], v3 offset:47616
	s_waitcnt lgkmcnt(2)
	v_mfma_f32_32x32x16_bf16 v[68:83], v[148:151], v[156:159], v[68:83]
	ds_read_b64_tr_b16 v[156:157], v3 offset:44032
	ds_read_b64_tr_b16 v[158:159], v3 offset:48128
	s_waitcnt lgkmcnt(2)
	v_mfma_f32_32x32x16_bf16 v[52:67], v[148:151], v[152:155], v[52:67]
	ds_read_b64_tr_b16 v[152:153], v3 offset:44544
	ds_read_b64_tr_b16 v[154:155], v3 offset:48640
	ds_read_b128 v[180:183], v225 offset:4096
	ds_read_b128 v[184:187], v226 offset:4096
	ds_read_b128 v[192:195], v227 offset:4096
	ds_read_b128 v[188:191], v228 offset:4096
	s_waitcnt lgkmcnt(6)
	v_mfma_f32_32x32x16_bf16 v[36:51], v[148:151], v[156:159], v[36:51]
	s_waitcnt lgkmcnt(4)
	v_mfma_f32_32x32x16_bf16 v[20:35], v[148:151], v[152:155], v[20:35]
	s_barrier
	s_setprio 1
	s_waitcnt lgkmcnt(3)
	v_mfma_i32_32x32x32_i8 v[148:163], v[180:183], v[164:167], v[132:147]
	s_waitcnt lgkmcnt(2)
	v_mfma_i32_32x32x32_i8 v[148:163], v[184:187], v[168:171], v[148:163]
	s_waitcnt lgkmcnt(1)
	v_mfma_i32_32x32x32_i8 v[148:163], v[192:195], v[172:175], v[148:163]
	ds_read_b64_tr_b16 v[184:185], v3 offset:49152
	ds_read_b64_tr_b16 v[186:187], v3 offset:53248
	s_waitcnt lgkmcnt(2)
	v_mfma_i32_32x32x32_i8 v[148:163], v[188:191], v[176:179], v[148:163]
	ds_read_b64_tr_b16 v[180:181], v3 offset:49664
	ds_read_b64_tr_b16 v[182:183], v3 offset:53760
	s_nop 9
	v_max3_f32 v188, v148, v149, v150
	v_max3_f32 v189, v151, v152, v153
	v_max3_f32 v190, v154, v155, v156
	v_max3_f32 v191, v157, v158, v159
	v_max3_f32 v192, v160, v161, v162
	v_max3_f32 v188, v188, v189, v190
	v_max3_f32 v191, v191, v192, v163
	v_max_f32_e32 v188, v188, v191
	v_add_f32_e32 v188, 0xcb400000, v188
	v_fma_f32 v189, v207, v188, -v237
	v_cmp_gt_f32_e32 vcc, v189, v220
	s_cbranch_vccnz .Lv2_rare_h2

.Lv2_back_h3:
	v_mul_f32_e32 v189, v221, v208
	v_fma_f32 v190, s100, v189, v255
	v_fma_f32 v148, v148, v189, -v190
	v_fma_f32 v149, v149, v189, -v190
	v_exp_f32_e32 v148, v148
	v_fma_f32 v150, v150, v189, -v190
	v_exp_f32_e32 v149, v149
	v_fma_f32 v151, v151, v189, -v190
	v_exp_f32_e32 v150, v150
	v_fma_f32 v152, v152, v189, -v190
	v_exp_f32_e32 v151, v151
	v_fma_f32 v153, v153, v189, -v190
	v_exp_f32_e32 v152, v152
	v_fma_f32 v154, v154, v189, -v190
	v_exp_f32_e32 v153, v153
	v_fma_f32 v155, v155, v189, -v190
	v_exp_f32_e32 v154, v154
	v_fma_f32 v156, v156, v189, -v190
	v_exp_f32_e32 v155, v155
	v_fma_f32 v157, v157, v189, -v190
	v_exp_f32_e32 v156, v156
	v_fma_f32 v158, v158, v189, -v190
	v_exp_f32_e32 v157, v157
	v_fma_f32 v159, v159, v189, -v190
	v_exp_f32_e32 v158, v158
	v_fma_f32 v160, v160, v189, -v190
	v_exp_f32_e32 v159, v159
	v_fma_f32 v161, v161, v189, -v190
	v_exp_f32_e32 v160, v160
	v_fma_f32 v162, v162, v189, -v190
	v_exp_f32_e32 v161, v161
	v_fma_f32 v163, v163, v189, -v190
	v_exp_f32_e32 v162, v162
	v_exp_f32_e32 v163, v163
	v_add_f32_e32 v188, v148, v149
	v_add_f32_e32 v189, v150, v151
	v_add_f32_e32 v190, v152, v153
	v_add_f32_e32 v191, v154, v155
	v_add_f32_e32 v192, v156, v157
	v_add_f32_e32 v193, v158, v159
	v_add_f32_e32 v194, v160, v161
	v_add_f32_e32 v195, v162, v163
	v_add_f32_e32 v188, v188, v189
	v_add_f32_e32 v190, v190, v191
	v_add_f32_e32 v192, v192, v193
	v_add_f32_e32 v194, v194, v195
	v_add_f32_e32 v188, v188, v190
	v_add_f32_e32 v192, v192, v194
	v_add_f32_e32 v188, v188, v192
	v_add_f32_e32 v224, v224, v188
	v_cvt_pk_bf16_f32 v155, v154, v155
	v_cvt_pk_bf16_f32 v154, v152, v153
	v_cvt_pk_bf16_f32 v152, v148, v149
	v_cvt_pk_bf16_f32 v153, v150, v151
	v_cvt_pk_bf16_f32 v148, v156, v157
	v_cvt_pk_bf16_f32 v149, v158, v159
	v_cvt_pk_bf16_f32 v150, v160, v161
	v_cvt_pk_bf16_f32 v151, v162, v163
	s_barrier
	s_setprio 0
	s_waitcnt lgkmcnt(2)
	v_mfma_f32_32x32x16_bf16 v[4:19], v[152:155], v[184:187], v[4:19]
	ds_read_b64_tr_b16 v[156:157], v222 offset:33792
	ds_read_b64_tr_b16 v[158:159], v222 offset:37888
	s_waitcnt lgkmcnt(2)
	v_mfma_f32_32x32x16_bf16 v[116:131], v[152:155], v[180:183], v[116:131]
	ds_read_b64_tr_b16 v[160:161], v222 offset:34304
	ds_read_b64_tr_b16 v[162:163], v222 offset:38400
	s_add_i32 m0, s83, 0
	s_nop 0
	global_load_lds_dwordx4 v200, s[86:87]
	s_waitcnt lgkmcnt(2)
	v_mfma_f32_32x32x16_bf16 v[100:115], v[152:155], v[156:159], v[100:115]
	ds_read_b64_tr_b16 v[156:157], v222 offset:34816
	ds_read_b64_tr_b16 v[158:159], v222 offset:38912
	s_waitcnt lgkmcnt(2)
	v_mfma_f32_32x32x16_bf16 v[84:99], v[152:155], v[160:163], v[84:99]
	ds_read_b64_tr_b16 v[160:161], v222 offset:35328
	ds_read_b64_tr_b16 v[162:163], v222 offset:39424
	s_add_i32 m0, s82, 0
	s_nop 0
	global_load_lds_dwordx4 v204, s[2:3]
	s_waitcnt lgkmcnt(2)
	v_mfma_f32_32x32x16_bf16 v[68:83], v[152:155], v[156:159], v[68:83]
	ds_read_b64_tr_b16 v[156:157], v222 offset:35840
	ds_read_b64_tr_b16 v[158:159], v222 offset:39936
	s_waitcnt lgkmcnt(2)
	v_mfma_f32_32x32x16_bf16 v[52:67], v[152:155], v[160:163], v[52:67]
	ds_read_b64_tr_b16 v[160:161], v222 offset:36352
	ds_read_b64_tr_b16 v[162:163], v222 offset:40448
	s_add_u32 s2, s2, 0x80
	s_addc_u32 s3, s3, 0
	s_add_i32 m0, s82, 0x400
	s_nop 0
	global_load_lds_dwordx4 v204, s[2:3]
	s_waitcnt lgkmcnt(2)
	v_mfma_f32_32x32x16_bf16 v[36:51], v[152:155], v[156:159], v[36:51]
	ds_read_b64_tr_b16 v[156:157], v222 offset:40960
	ds_read_b64_tr_b16 v[158:159], v222 offset:45056
	s_waitcnt lgkmcnt(2)
	v_mfma_f32_32x32x16_bf16 v[20:35], v[152:155], v[160:163], v[20:35]
	ds_read_b64_tr_b16 v[152:153], v222 offset:41472
	ds_read_b64_tr_b16 v[154:155], v222 offset:45568
	s_add_u32 s2, s2, 0x80
	s_addc_u32 s3, s3, 0
	s_add_i32 m0, s82, 0x800
	s_nop 0
	global_load_lds_dwordx4 v204, s[2:3]
	s_waitcnt lgkmcnt(2)
	v_mfma_f32_32x32x16_bf16 v[4:19], v[148:151], v[156:159], v[4:19]
	ds_read_b64_tr_b16 v[156:157], v222 offset:41984
	ds_read_b64_tr_b16 v[158:159], v222 offset:46080
	s_waitcnt lgkmcnt(2)
	v_mfma_f32_32x32x16_bf16 v[116:131], v[148:151], v[152:155], v[116:131]
	ds_read_b64_tr_b16 v[152:153], v222 offset:42496
	ds_read_b64_tr_b16 v[154:155], v222 offset:46592
	s_add_u32 s2, s2, 0x80
	s_addc_u32 s3, s3, 0
	s_add_i32 m0, s82, 0xc00
	s_nop 0
	global_load_lds_dwordx4 v204, s[2:3]
	s_waitcnt lgkmcnt(2)
	v_mfma_f32_32x32x16_bf16 v[100:115], v[148:151], v[156:159], v[100:115]
	ds_read_b64_tr_b16 v[156:157], v222 offset:43008
	ds_read_b64_tr_b16 v[158:159], v222 offset:47104
	s_waitcnt lgkmcnt(2)
	v_mfma_f32_32x32x16_bf16 v[84:99], v[148:151], v[152:155], v[84:99]
	ds_read_b64_tr_b16 v[152:153], v222 offset:43520
	ds_read_b64_tr_b16 v[154:155], v222 offset:47616
	s_waitcnt lgkmcnt(2)
	v_mfma_f32_32x32x16_bf16 v[68:83], v[148:151], v[156:159], v[68:83]
	ds_read_b64_tr_b16 v[156:157], v222 offset:44032
	ds_read_b64_tr_b16 v[158:159], v222 offset:48128
	s_waitcnt lgkmcnt(2)
	v_mfma_f32_32x32x16_bf16 v[52:67], v[148:151], v[152:155], v[52:67]
	ds_read_b64_tr_b16 v[152:153], v222 offset:44544
	ds_read_b64_tr_b16 v[154:155], v222 offset:48640
	ds_read_b128 v[180:183], v225 offset:20480
	ds_read_b128 v[184:187], v226 offset:20480
	ds_read_b128 v[192:195], v227 offset:20480
	ds_read_b128 v[188:191], v228 offset:20480
	s_waitcnt lgkmcnt(6)
	v_mfma_f32_32x32x16_bf16 v[36:51], v[148:151], v[156:159], v[36:51]
	s_waitcnt lgkmcnt(4)
	v_mfma_f32_32x32x16_bf16 v[20:35], v[148:151], v[152:155], v[20:35]
	s_barrier
	s_setprio 1
	s_waitcnt lgkmcnt(3)
	v_mfma_i32_32x32x32_i8 v[148:163], v[180:183], v[164:167], v[132:147]
	s_waitcnt lgkmcnt(2)
	v_mfma_i32_32x32x32_i8 v[148:163], v[184:187], v[168:171], v[148:163]
	s_waitcnt lgkmcnt(1)
	v_mfma_i32_32x32x32_i8 v[148:163], v[192:195], v[172:175], v[148:163]
	ds_read_b64_tr_b16 v[184:185], v222 offset:49152
	ds_read_b64_tr_b16 v[186:187], v222 offset:53248
	s_waitcnt lgkmcnt(2)
	v_mfma_i32_32x32x32_i8 v[148:163], v[188:191], v[176:179], v[148:163]
	ds_read_b64_tr_b16 v[180:181], v222 offset:49664
	ds_read_b64_tr_b16 v[182:183], v222 offset:53760
	s_nop 9
	v_max3_f32 v188, v148, v149, v150
	v_max3_f32 v189, v151, v152, v153
	v_max3_f32 v190, v154, v155, v156
	v_max3_f32 v191, v157, v158, v159
	v_max3_f32 v192, v160, v161, v162
	v_max3_f32 v188, v188, v189, v190
	v_max3_f32 v191, v191, v192, v163
	v_max_f32_e32 v188, v188, v191
	v_add_f32_e32 v188, 0xcb400000, v188
	v_fma_f32 v189, v236, v188, -v237
	v_cmp_gt_f32_e32 vcc, v189, v220
	s_cbranch_vccnz .Lv2_rare_h4
